# combine loop pipelined two deep with exact vmcnt counts (7 in steady state) and store-data WAR wait states
# speedup vs baseline: 1.0035x; 1.0008x over previous
; __device__ __forceinline__ unsigned cvt_pk_bf16(float lo, float hi) { unsigned r; asm volatile("v_cvt_pk_bf16_f32 %0, %1, %2" : "=v"(r) : "v"(lo), "v"(hi)); return r; }
; __device__ __forceinline__ float bf_lo(unsigned w) { return __uint_as_float(w << 16); }
; __device__ __forceinline__ float bf_hi(unsigned w) { return __uint_as_float(w & 0xffff0000u); }
; __device__ __forceinline__ void combine_phase(const bf16_t* __restrict__ og, const float* __restrict__ lse, bf16_t* __restrict__ dst, int G, int bid) {
;     ...
;     for (int idx = bid * NTHR + threadIdx.x; idx < SEQ * 256; idx += G * NTHR) {
;         const int t = idx >> 8, oc = idx & 255, h = oc >> 4;
;         const float l0 = lse[(size_t)t * 16 + h], l1 = lse[(size_t)SEQ * 16 + (size_t)t * 16 + h], l2 = lse[(size_t)2 * SEQ * 16 + (size_t)t * 16 + h];
;         const float mx = fmaxf(l0, fmaxf(l1, l2));
;         float w0 = __expf(l0 - mx), w1 = __expf(l1 - mx), w2 = __expf(l2 - mx);
;         const float inv = 1.0f / (w0 + w1 + w2); w0 *= inv; w1 *= inv; w2 *= inv;
;         const size_t off = (size_t)t * DM + oc * 8;
;         const u32x4 a = *(const u32x4*)(og + off), b = *(const u32x4*)(og + (size_t)SEQ * DM + off), c = *(const u32x4*)(og + (size_t)2 * SEQ * DM + off);
;         u32x4 w;
;         w.x = cvt_pk_bf16(w0 * bf_lo(a.x) + w1 * bf_lo(b.x) + w2 * bf_lo(c.x), w0 * bf_hi(a.x) + w1 * bf_hi(b.x) + w2 * bf_hi(c.x));
;         w.y = cvt_pk_bf16(w0 * bf_lo(a.y) + w1 * bf_lo(b.y) + w2 * bf_lo(c.y), w0 * bf_hi(a.y) + w1 * bf_hi(b.y) + w2 * bf_hi(c.y));
;         w.z = cvt_pk_bf16(w0 * bf_lo(a.z) + w1 * bf_lo(b.z) + w2 * bf_lo(c.z), w0 * bf_hi(a.z) + w1 * bf_hi(b.z) + w2 * bf_hi(c.z));
;         w.w = cvt_pk_bf16(w0 * bf_lo(a.w) + w1 * bf_lo(b.w) + w2 * bf_lo(c.w), w0 * bf_hi(a.w) + w1 * bf_hi(b.w) + w2 * bf_hi(c.w));
;         *(u32x4*)(dst + off) = w;
.LBB0_1292:
	s_cmp_lt_i32 s84, 15
	s_cselect_b64 s[2:3], -1, 0
	s_and_b64 s[2:3], s[2:3], s[0:1]
	s_andn2_b64 vcc, exec, s[2:3]
	s_cbranch_vccnz .LBB0_1301
	s_mov_b32 s0, 0x400000
	v_cmp_gt_i32_e32 vcc, s0, v225
	s_and_saveexec_b64 s[0:1], vcc
	v_readlane_b32 s14, v252, 11
	v_readlane_b32 s15, v252, 12
	s_cbranch_execz .LBB0_1296
	s_waitcnt lgkmcnt(0)
	s_add_u32 s4, s82, 0x1e680000
	s_addc_u32 s5, s83, 0
	s_add_u32 s6, s82, 0x22680000
	s_waitcnt vmcnt(2)
	v_bfe_u32 v0, v224, 4, 4
	v_mov_b32_e32 v2, 3
	s_addc_u32 s7, s83, 0
	s_lshl_b32 s10, s78, 9
	v_mov_b32_e32 v1, 0
	v_lshlrev_b32_sdwa v2, v2, v224 dst_sel:DWORD dst_unused:UNUSED_PAD src0_sel:DWORD src1_sel:BYTE_0
	s_mov_b64 s[8:9], 0
	v_lshlrev_b32_e32 v0, 2, v0
	s_mov_b32 s11, 0x3fffff
	s_cmpk_eq_u32 s78, 0x100
	s_cbranch_scc0 .LBB0_1295
	s_mov_b32 s99, 15
	v_ashrrev_i32_e32 v4, 8, v225
	v_ashrrev_i32_e32 v5, 31, v4
	v_lshlrev_b64 v[6:7], 6, v[4:5]
	v_add_u32_e32 v225, s10, v225
	v_lshl_add_u64 v[6:7], s[48:49], 0, v[6:7]
	v_lshlrev_b64 v[4:5], 12, v[4:5]
	v_lshl_add_u64 v[12:13], v[6:7], 0, v[0:1]
	v_lshl_or_b32 v4, v2, 1, v4
	v_add_co_u32_e32 v20, vcc, 0x100000, v12
	v_lshl_add_u64 v[8:9], s[4:5], 0, v[4:5]
	s_nop 0
	v_addc_co_u32_e32 v21, vcc, 0, v13, vcc
	v_lshl_add_u64 v[16:17], s[56:57], 0, v[4:5]
	v_lshl_add_u64 v[10:11], s[6:7], 0, v[4:5]
	v_lshl_add_u64 v[18:19], s[14:15], 0, v[4:5]
	global_load_dwordx4 v[4:7], v[8:9], off
	global_load_dword v3, v[12:13], off
	v_add_co_u32_e32 v22, vcc, 0x200000, v12
	global_load_dwordx4 v[8:11], v[10:11], off
	s_nop 0
	v_addc_co_u32_e32 v23, vcc, 0, v13, vcc
	global_load_dword v26, v[20:21], off
	global_load_dword v27, v[22:23], off
	global_load_dwordx4 v[12:15], v[16:17], off
	v_ashrrev_i32_e32 v68, 8, v225
	v_ashrrev_i32_e32 v69, 31, v68
	v_lshlrev_b64 v[70:71], 6, v[68:69]
	v_add_u32_e32 v225, s10, v225
	v_lshl_add_u64 v[70:71], s[48:49], 0, v[70:71]
	v_lshlrev_b64 v[68:69], 12, v[68:69]
	v_lshl_add_u64 v[76:77], v[70:71], 0, v[0:1]
	v_lshl_or_b32 v68, v2, 1, v68
	v_add_co_u32_e32 v84, vcc, 0x100000, v76
	v_lshl_add_u64 v[72:73], s[4:5], 0, v[68:69]
	s_nop 0
	v_addc_co_u32_e32 v85, vcc, 0, v77, vcc
	v_lshl_add_u64 v[80:81], s[56:57], 0, v[68:69]
	v_lshl_add_u64 v[74:75], s[6:7], 0, v[68:69]
	v_lshl_add_u64 v[82:83], s[14:15], 0, v[68:69]
	global_load_dwordx4 v[68:71], v[72:73], off
	global_load_dword v67, v[76:77], off
	v_add_co_u32_e32 v86, vcc, 0x200000, v76
	global_load_dwordx4 v[72:75], v[74:75], off
	s_nop 0
	v_addc_co_u32_e32 v87, vcc, 0, v77, vcc
	global_load_dword v90, v[84:85], off
	global_load_dword v91, v[86:87], off
	global_load_dwordx4 v[76:79], v[80:81], off
	s_waitcnt vmcnt(6)
	v_lshlrev_b32_e32 v30, 16, v5
	v_and_b32_e32 v31, 0xffff0000, v5
	v_lshlrev_b32_e32 v34, 16, v7
	v_and_b32_e32 v35, 0xffff0000, v7
	v_lshlrev_b32_e32 v28, 16, v4
	v_and_b32_e32 v29, 0xffff0000, v4
	v_max3_f32 v36, v3, v26, v27
	v_lshlrev_b32_e32 v5, 16, v12
	v_and_b32_e32 v7, 0xffff0000, v12
	v_sub_f32_e32 v3, v3, v36
	v_sub_f32_e32 v12, v26, v36
	v_lshlrev_b32_e32 v32, 16, v6
	v_and_b32_e32 v33, 0xffff0000, v6
	v_lshlrev_b32_e32 v4, 16, v8
	v_and_b32_e32 v6, 0xffff0000, v8
	v_lshlrev_b32_e32 v8, 16, v9
	v_and_b32_e32 v16, 0xffff0000, v9
	v_lshlrev_b32_e32 v9, 16, v13
	v_and_b32_e32 v17, 0xffff0000, v13
	v_sub_f32_e32 v13, v27, v36
	v_mul_f32_e32 v3, 0x3fb8aa3b, v3
	v_mul_f32_e32 v12, 0x3fb8aa3b, v12
	v_lshlrev_b32_e32 v22, 16, v11
	v_and_b32_e32 v24, 0xffff0000, v11
	v_lshlrev_b32_e32 v21, 16, v14
	v_and_b32_e32 v11, 0xffff0000, v14
	v_mul_f32_e32 v14, 0x3fb8aa3b, v13
	v_exp_f32_e32 v13, v3
	v_exp_f32_e32 v3, v12
	v_exp_f32_e32 v12, v14
	v_lshlrev_b32_e32 v23, 16, v15
	v_and_b32_e32 v25, 0xffff0000, v15
	v_add_f32_e32 v14, v13, v3
	v_add_f32_e32 v14, v12, v14
	v_div_scale_f32 v15, s[12:13], v14, v14, 1.0
	v_rcp_f32_e32 v27, v15
	v_div_scale_f32 v26, vcc, 1.0, v14, 1.0
	v_lshlrev_b32_e32 v20, 16, v10
	v_fma_f32 v36, -v15, v27, 1.0
	v_fmac_f32_e32 v27, v36, v27
	v_mul_f32_e32 v36, v26, v27
	v_fma_f32 v37, -v15, v36, v26
	v_fmac_f32_e32 v36, v37, v27
	v_fma_f32 v15, -v15, v36, v26
	v_div_fmas_f32 v15, v15, v27, v36
	v_div_fixup_f32 v14, v15, v14, 1.0
	v_pk_mul_f32 v[12:13], v[12:13], v[14:15] op_sel_hi:[1,0]
	v_and_b32_e32 v10, 0xffff0000, v10
	v_mul_f32_e32 v3, v3, v14
	v_pk_mul_f32 v[4:5], v[12:13], v[4:5]
	v_pk_mul_f32 v[6:7], v[12:13], v[6:7]
	v_pk_mul_f32 v[8:9], v[12:13], v[8:9]
	v_pk_mul_f32 v[14:15], v[12:13], v[16:17]
	v_pk_mul_f32 v[16:17], v[12:13], v[20:21]
	v_pk_mul_f32 v[10:11], v[12:13], v[10:11]
	v_pk_mul_f32 v[20:21], v[12:13], v[22:23]
	v_pk_mul_f32 v[12:13], v[12:13], v[24:25]
	v_fma_f32 v5, v3, v28, v5
	v_fma_f32 v7, v3, v29, v7
	v_fma_f32 v9, v3, v30, v9
	v_fma_f32 v15, v3, v31, v15
	v_fma_f32 v17, v3, v32, v17
	v_fma_f32 v11, v3, v33, v11
	v_fma_f32 v21, v3, v34, v21
	v_fma_f32 v3, v3, v35, v13
	v_add_f32_e32 v4, v4, v5
	v_add_f32_e32 v5, v6, v7
	v_add_f32_e32 v6, v8, v9
	v_add_f32_e32 v7, v14, v15
	v_add_f32_e32 v8, v16, v17
	v_add_f32_e32 v9, v10, v11
	v_add_f32_e32 v10, v20, v21
	v_add_f32_e32 v3, v12, v3
	v_cvt_pk_bf16_f32 v4, v4, v5
	v_cvt_pk_bf16_f32 v5, v6, v7
	v_cvt_pk_bf16_f32 v6, v8, v9
	v_cvt_pk_bf16_f32 v7, v10, v3
	global_store_dwordx4 v[18:19], v[4:7], off
; __device__ __forceinline__ unsigned cvt_pk_bf16(float lo, float hi) { unsigned r; asm volatile("v_cvt_pk_bf16_f32 %0, %1, %2" : "=v"(r) : "v"(lo), "v"(hi)); return r; }
; __device__ __forceinline__ float bf_lo(unsigned w) { return __uint_as_float(w << 16); }
; __device__ __forceinline__ float bf_hi(unsigned w) { return __uint_as_float(w & 0xffff0000u); }
; __device__ __forceinline__ void combine_phase(const bf16_t* __restrict__ og, const float* __restrict__ lse, bf16_t* __restrict__ dst, int G, int bid) {
;     ...
;     for (int idx = bid * NTHR + threadIdx.x; idx < SEQ * 256; idx += G * NTHR) {
;         const int t = idx >> 8, oc = idx & 255, h = oc >> 4;
;         const float l0 = lse[(size_t)t * 16 + h], l1 = lse[(size_t)SEQ * 16 + (size_t)t * 16 + h], l2 = lse[(size_t)2 * SEQ * 16 + (size_t)t * 16 + h];
;         const float mx = fmaxf(l0, fmaxf(l1, l2));
;         float w0 = __expf(l0 - mx), w1 = __expf(l1 - mx), w2 = __expf(l2 - mx);
;         const float inv = 1.0f / (w0 + w1 + w2); w0 *= inv; w1 *= inv; w2 *= inv;
;         const size_t off = (size_t)t * DM + oc * 8;
;         const u32x4 a = *(const u32x4*)(og + off), b = *(const u32x4*)(og + (size_t)SEQ * DM + off), c = *(const u32x4*)(og + (size_t)2 * SEQ * DM + off);
;         u32x4 w;
;         w.x = cvt_pk_bf16(w0 * bf_lo(a.x) + w1 * bf_lo(b.x) + w2 * bf_lo(c.x), w0 * bf_hi(a.x) + w1 * bf_hi(b.x) + w2 * bf_hi(c.x));
;         w.y = cvt_pk_bf16(w0 * bf_lo(a.y) + w1 * bf_lo(b.y) + w2 * bf_lo(c.y), w0 * bf_hi(a.y) + w1 * bf_hi(b.y) + w2 * bf_hi(c.y));
;         w.z = cvt_pk_bf16(w0 * bf_lo(a.z) + w1 * bf_lo(b.z) + w2 * bf_lo(c.z), w0 * bf_hi(a.z) + w1 * bf_hi(b.z) + w2 * bf_hi(c.z));
;         w.w = cvt_pk_bf16(w0 * bf_lo(a.w) + w1 * bf_lo(b.w) + w2 * bf_lo(c.w), w0 * bf_hi(a.w) + w1 * bf_hi(b.w) + w2 * bf_hi(c.w));
;         *(u32x4*)(dst + off) = w;
.Lcmb_loop:
	s_nop 1
	v_ashrrev_i32_e32 v4, 8, v225
	v_ashrrev_i32_e32 v5, 31, v4
	v_lshlrev_b64 v[6:7], 6, v[4:5]
	v_add_u32_e32 v225, s10, v225
	v_lshl_add_u64 v[6:7], s[48:49], 0, v[6:7]
	v_lshlrev_b64 v[4:5], 12, v[4:5]
	v_lshl_add_u64 v[12:13], v[6:7], 0, v[0:1]
	v_lshl_or_b32 v4, v2, 1, v4
	v_add_co_u32_e32 v20, vcc, 0x100000, v12
	v_lshl_add_u64 v[8:9], s[4:5], 0, v[4:5]
	s_nop 0
	v_addc_co_u32_e32 v21, vcc, 0, v13, vcc
	v_lshl_add_u64 v[16:17], s[56:57], 0, v[4:5]
	v_lshl_add_u64 v[10:11], s[6:7], 0, v[4:5]
	v_lshl_add_u64 v[18:19], s[14:15], 0, v[4:5]
	global_load_dwordx4 v[4:7], v[8:9], off
	global_load_dword v3, v[12:13], off
	v_add_co_u32_e32 v22, vcc, 0x200000, v12
	global_load_dwordx4 v[8:11], v[10:11], off
	s_nop 0
	v_addc_co_u32_e32 v23, vcc, 0, v13, vcc
	global_load_dword v26, v[20:21], off
	global_load_dword v27, v[22:23], off
	global_load_dwordx4 v[12:15], v[16:17], off
	s_waitcnt vmcnt(7)
	v_lshlrev_b32_e32 v94, 16, v69
	v_and_b32_e32 v95, 0xffff0000, v69
	v_lshlrev_b32_e32 v98, 16, v71
	v_and_b32_e32 v99, 0xffff0000, v71
	v_lshlrev_b32_e32 v92, 16, v68
	v_and_b32_e32 v93, 0xffff0000, v68
	v_max3_f32 v100, v67, v90, v91
	v_lshlrev_b32_e32 v69, 16, v76
	v_and_b32_e32 v71, 0xffff0000, v76
	v_sub_f32_e32 v67, v67, v100
	v_sub_f32_e32 v76, v90, v100
	v_lshlrev_b32_e32 v96, 16, v70
	v_and_b32_e32 v97, 0xffff0000, v70
	v_lshlrev_b32_e32 v68, 16, v72
	v_and_b32_e32 v70, 0xffff0000, v72
	v_lshlrev_b32_e32 v72, 16, v73
	v_and_b32_e32 v80, 0xffff0000, v73
	v_lshlrev_b32_e32 v73, 16, v77
	v_and_b32_e32 v81, 0xffff0000, v77
	v_sub_f32_e32 v77, v91, v100
	v_mul_f32_e32 v67, 0x3fb8aa3b, v67
	v_mul_f32_e32 v76, 0x3fb8aa3b, v76
	v_lshlrev_b32_e32 v86, 16, v75
	v_and_b32_e32 v88, 0xffff0000, v75
	v_lshlrev_b32_e32 v85, 16, v78
	v_and_b32_e32 v75, 0xffff0000, v78
	v_mul_f32_e32 v78, 0x3fb8aa3b, v77
	v_exp_f32_e32 v77, v67
	v_exp_f32_e32 v67, v76
	v_exp_f32_e32 v76, v78
	v_lshlrev_b32_e32 v87, 16, v79
	v_and_b32_e32 v89, 0xffff0000, v79
	v_add_f32_e32 v78, v77, v67
	v_add_f32_e32 v78, v76, v78
	v_div_scale_f32 v79, s[12:13], v78, v78, 1.0
	v_rcp_f32_e32 v91, v79
	v_div_scale_f32 v90, vcc, 1.0, v78, 1.0
	v_lshlrev_b32_e32 v84, 16, v74
	v_fma_f32 v100, -v79, v91, 1.0
	v_fmac_f32_e32 v91, v100, v91
	v_mul_f32_e32 v100, v90, v91
	v_fma_f32 v101, -v79, v100, v90
	v_fmac_f32_e32 v100, v101, v91
	v_fma_f32 v79, -v79, v100, v90
	v_div_fmas_f32 v79, v79, v91, v100
	v_div_fixup_f32 v78, v79, v78, 1.0
	v_pk_mul_f32 v[76:77], v[76:77], v[78:79] op_sel_hi:[1,0]
	v_and_b32_e32 v74, 0xffff0000, v74
	v_mul_f32_e32 v67, v67, v78
	v_pk_mul_f32 v[68:69], v[76:77], v[68:69]
	v_pk_mul_f32 v[70:71], v[76:77], v[70:71]
	v_pk_mul_f32 v[72:73], v[76:77], v[72:73]
	v_pk_mul_f32 v[78:79], v[76:77], v[80:81]
	v_pk_mul_f32 v[80:81], v[76:77], v[84:85]
	v_pk_mul_f32 v[74:75], v[76:77], v[74:75]
	v_pk_mul_f32 v[84:85], v[76:77], v[86:87]
	v_pk_mul_f32 v[76:77], v[76:77], v[88:89]
	v_fma_f32 v69, v67, v92, v69
	v_fma_f32 v71, v67, v93, v71
	v_fma_f32 v73, v67, v94, v73
	v_fma_f32 v79, v67, v95, v79
	v_fma_f32 v81, v67, v96, v81
	v_fma_f32 v75, v67, v97, v75
	v_fma_f32 v85, v67, v98, v85
	v_fma_f32 v67, v67, v99, v77
	v_add_f32_e32 v68, v68, v69
	v_add_f32_e32 v69, v70, v71
	v_add_f32_e32 v70, v72, v73
	v_add_f32_e32 v71, v78, v79
	v_add_f32_e32 v72, v80, v81
	v_add_f32_e32 v73, v74, v75
	v_add_f32_e32 v74, v84, v85
	v_add_f32_e32 v67, v76, v67
	v_cvt_pk_bf16_f32 v68, v68, v69
	v_cvt_pk_bf16_f32 v69, v70, v71
	v_cvt_pk_bf16_f32 v70, v72, v73
	v_cvt_pk_bf16_f32 v71, v74, v67
	global_store_dwordx4 v[82:83], v[68:71], off
	s_nop 1
	v_ashrrev_i32_e32 v68, 8, v225
	v_ashrrev_i32_e32 v69, 31, v68
	v_lshlrev_b64 v[70:71], 6, v[68:69]
	v_add_u32_e32 v225, s10, v225
	v_lshl_add_u64 v[70:71], s[48:49], 0, v[70:71]
	v_lshlrev_b64 v[68:69], 12, v[68:69]
	v_lshl_add_u64 v[76:77], v[70:71], 0, v[0:1]
	v_lshl_or_b32 v68, v2, 1, v68
	v_add_co_u32_e32 v84, vcc, 0x100000, v76
	v_lshl_add_u64 v[72:73], s[4:5], 0, v[68:69]
	s_nop 0
	v_addc_co_u32_e32 v85, vcc, 0, v77, vcc
	v_lshl_add_u64 v[80:81], s[56:57], 0, v[68:69]
	v_lshl_add_u64 v[74:75], s[6:7], 0, v[68:69]
	v_lshl_add_u64 v[82:83], s[14:15], 0, v[68:69]
	global_load_dwordx4 v[68:71], v[72:73], off
	global_load_dword v67, v[76:77], off
	v_add_co_u32_e32 v86, vcc, 0x200000, v76
	global_load_dwordx4 v[72:75], v[74:75], off
	s_nop 0
	v_addc_co_u32_e32 v87, vcc, 0, v77, vcc
	global_load_dword v90, v[84:85], off
	global_load_dword v91, v[86:87], off
	global_load_dwordx4 v[76:79], v[80:81], off
	s_waitcnt vmcnt(7)
; __device__ __forceinline__ unsigned cvt_pk_bf16(float lo, float hi) { unsigned r; asm volatile("v_cvt_pk_bf16_f32 %0, %1, %2" : "=v"(r) : "v"(lo), "v"(hi)); return r; }
; __device__ __forceinline__ float bf_lo(unsigned w) { return __uint_as_float(w << 16); }
; __device__ __forceinline__ float bf_hi(unsigned w) { return __uint_as_float(w & 0xffff0000u); }
; __device__ __forceinline__ void combine_phase(const bf16_t* __restrict__ og, const float* __restrict__ lse, bf16_t* __restrict__ dst, int G, int bid) {
;     ...
;     for (int idx = bid * NTHR + threadIdx.x; idx < SEQ * 256; idx += G * NTHR) {
;         const int t = idx >> 8, oc = idx & 255, h = oc >> 4;
;         const float l0 = lse[(size_t)t * 16 + h], l1 = lse[(size_t)SEQ * 16 + (size_t)t * 16 + h], l2 = lse[(size_t)2 * SEQ * 16 + (size_t)t * 16 + h];
;         const float mx = fmaxf(l0, fmaxf(l1, l2));
;         float w0 = __expf(l0 - mx), w1 = __expf(l1 - mx), w2 = __expf(l2 - mx);
;         const float inv = 1.0f / (w0 + w1 + w2); w0 *= inv; w1 *= inv; w2 *= inv;
;         const size_t off = (size_t)t * DM + oc * 8;
;         const u32x4 a = *(const u32x4*)(og + off), b = *(const u32x4*)(og + (size_t)SEQ * DM + off), c = *(const u32x4*)(og + (size_t)2 * SEQ * DM + off);
;         u32x4 w;
;         w.x = cvt_pk_bf16(w0 * bf_lo(a.x) + w1 * bf_lo(b.x) + w2 * bf_lo(c.x), w0 * bf_hi(a.x) + w1 * bf_hi(b.x) + w2 * bf_hi(c.x));
;         w.y = cvt_pk_bf16(w0 * bf_lo(a.y) + w1 * bf_lo(b.y) + w2 * bf_lo(c.y), w0 * bf_hi(a.y) + w1 * bf_hi(b.y) + w2 * bf_hi(c.y));
;         w.z = cvt_pk_bf16(w0 * bf_lo(a.z) + w1 * bf_lo(b.z) + w2 * bf_lo(c.z), w0 * bf_hi(a.z) + w1 * bf_hi(b.z) + w2 * bf_hi(c.z));
;         w.w = cvt_pk_bf16(w0 * bf_lo(a.w) + w1 * bf_lo(b.w) + w2 * bf_lo(c.w), w0 * bf_hi(a.w) + w1 * bf_hi(b.w) + w2 * bf_hi(c.w));
;         *(u32x4*)(dst + off) = w;
	v_lshlrev_b32_e32 v30, 16, v5
	v_and_b32_e32 v31, 0xffff0000, v5
	v_lshlrev_b32_e32 v34, 16, v7
	v_and_b32_e32 v35, 0xffff0000, v7
	v_lshlrev_b32_e32 v28, 16, v4
	v_and_b32_e32 v29, 0xffff0000, v4
	v_max3_f32 v36, v3, v26, v27
	v_lshlrev_b32_e32 v5, 16, v12
	v_and_b32_e32 v7, 0xffff0000, v12
	v_sub_f32_e32 v3, v3, v36
	v_sub_f32_e32 v12, v26, v36
	v_lshlrev_b32_e32 v32, 16, v6
	v_and_b32_e32 v33, 0xffff0000, v6
	v_lshlrev_b32_e32 v4, 16, v8
	v_and_b32_e32 v6, 0xffff0000, v8
	v_lshlrev_b32_e32 v8, 16, v9
	v_and_b32_e32 v16, 0xffff0000, v9
	v_lshlrev_b32_e32 v9, 16, v13
	v_and_b32_e32 v17, 0xffff0000, v13
	v_sub_f32_e32 v13, v27, v36
	v_mul_f32_e32 v3, 0x3fb8aa3b, v3
	v_mul_f32_e32 v12, 0x3fb8aa3b, v12
	v_lshlrev_b32_e32 v22, 16, v11
	v_and_b32_e32 v24, 0xffff0000, v11
	v_lshlrev_b32_e32 v21, 16, v14
	v_and_b32_e32 v11, 0xffff0000, v14
	v_mul_f32_e32 v14, 0x3fb8aa3b, v13
	v_exp_f32_e32 v13, v3
	v_exp_f32_e32 v3, v12
	v_exp_f32_e32 v12, v14
	v_lshlrev_b32_e32 v23, 16, v15
	v_and_b32_e32 v25, 0xffff0000, v15
	v_add_f32_e32 v14, v13, v3
	v_add_f32_e32 v14, v12, v14
	v_div_scale_f32 v15, s[12:13], v14, v14, 1.0
	v_rcp_f32_e32 v27, v15
	v_div_scale_f32 v26, vcc, 1.0, v14, 1.0
	v_lshlrev_b32_e32 v20, 16, v10
	v_fma_f32 v36, -v15, v27, 1.0
	v_fmac_f32_e32 v27, v36, v27
	v_mul_f32_e32 v36, v26, v27
	v_fma_f32 v37, -v15, v36, v26
	v_fmac_f32_e32 v36, v37, v27
	v_fma_f32 v15, -v15, v36, v26
	v_div_fmas_f32 v15, v15, v27, v36
	v_div_fixup_f32 v14, v15, v14, 1.0
	v_pk_mul_f32 v[12:13], v[12:13], v[14:15] op_sel_hi:[1,0]
	v_and_b32_e32 v10, 0xffff0000, v10
	v_mul_f32_e32 v3, v3, v14
	v_pk_mul_f32 v[4:5], v[12:13], v[4:5]
	v_pk_mul_f32 v[6:7], v[12:13], v[6:7]
	v_pk_mul_f32 v[8:9], v[12:13], v[8:9]
	v_pk_mul_f32 v[14:15], v[12:13], v[16:17]
	v_pk_mul_f32 v[16:17], v[12:13], v[20:21]
	v_pk_mul_f32 v[10:11], v[12:13], v[10:11]
	v_pk_mul_f32 v[20:21], v[12:13], v[22:23]
	v_pk_mul_f32 v[12:13], v[12:13], v[24:25]
	v_fma_f32 v5, v3, v28, v5
	v_fma_f32 v7, v3, v29, v7
	v_fma_f32 v9, v3, v30, v9
	v_fma_f32 v15, v3, v31, v15
	v_fma_f32 v17, v3, v32, v17
	v_fma_f32 v11, v3, v33, v11
	v_fma_f32 v21, v3, v34, v21
	v_fma_f32 v3, v3, v35, v13
	v_add_f32_e32 v4, v4, v5
	v_add_f32_e32 v5, v6, v7
	v_add_f32_e32 v6, v8, v9
	v_add_f32_e32 v7, v14, v15
	v_add_f32_e32 v8, v16, v17
	v_add_f32_e32 v9, v10, v11
	v_add_f32_e32 v10, v20, v21
	v_add_f32_e32 v3, v12, v3
	v_cvt_pk_bf16_f32 v4, v4, v5
	v_cvt_pk_bf16_f32 v5, v6, v7
	v_cvt_pk_bf16_f32 v6, v8, v9
	v_cvt_pk_bf16_f32 v7, v10, v3
	global_store_dwordx4 v[18:19], v[4:7], off
	s_sub_u32 s99, s99, 1
	s_cmp_lg_u32 s99, 0
	s_cbranch_scc1 .Lcmb_loop
	s_waitcnt vmcnt(1)
	v_lshlrev_b32_e32 v94, 16, v69
	v_and_b32_e32 v95, 0xffff0000, v69
	v_lshlrev_b32_e32 v98, 16, v71
	v_and_b32_e32 v99, 0xffff0000, v71
	v_lshlrev_b32_e32 v92, 16, v68
	v_and_b32_e32 v93, 0xffff0000, v68
	v_max3_f32 v100, v67, v90, v91
	v_lshlrev_b32_e32 v69, 16, v76
	v_and_b32_e32 v71, 0xffff0000, v76
	v_sub_f32_e32 v67, v67, v100
	v_sub_f32_e32 v76, v90, v100
	v_lshlrev_b32_e32 v96, 16, v70
	v_and_b32_e32 v97, 0xffff0000, v70
	v_lshlrev_b32_e32 v68, 16, v72
	v_and_b32_e32 v70, 0xffff0000, v72
	v_lshlrev_b32_e32 v72, 16, v73
	v_and_b32_e32 v80, 0xffff0000, v73
	v_lshlrev_b32_e32 v73, 16, v77
	v_and_b32_e32 v81, 0xffff0000, v77
	v_sub_f32_e32 v77, v91, v100
	v_mul_f32_e32 v67, 0x3fb8aa3b, v67
	v_mul_f32_e32 v76, 0x3fb8aa3b, v76
	v_lshlrev_b32_e32 v86, 16, v75
	v_and_b32_e32 v88, 0xffff0000, v75
	v_lshlrev_b32_e32 v85, 16, v78
	v_and_b32_e32 v75, 0xffff0000, v78
	v_mul_f32_e32 v78, 0x3fb8aa3b, v77
	v_exp_f32_e32 v77, v67
	v_exp_f32_e32 v67, v76
	v_exp_f32_e32 v76, v78
	v_lshlrev_b32_e32 v87, 16, v79
	v_and_b32_e32 v89, 0xffff0000, v79
	v_add_f32_e32 v78, v77, v67
	v_add_f32_e32 v78, v76, v78
	v_div_scale_f32 v79, s[12:13], v78, v78, 1.0
	v_rcp_f32_e32 v91, v79
	v_div_scale_f32 v90, vcc, 1.0, v78, 1.0
	v_lshlrev_b32_e32 v84, 16, v74
	v_fma_f32 v100, -v79, v91, 1.0
	v_fmac_f32_e32 v91, v100, v91
	v_mul_f32_e32 v100, v90, v91
	v_fma_f32 v101, -v79, v100, v90
	v_fmac_f32_e32 v100, v101, v91
	v_fma_f32 v79, -v79, v100, v90
	v_div_fmas_f32 v79, v79, v91, v100
	v_div_fixup_f32 v78, v79, v78, 1.0
	v_pk_mul_f32 v[76:77], v[76:77], v[78:79] op_sel_hi:[1,0]
	v_and_b32_e32 v74, 0xffff0000, v74
	v_mul_f32_e32 v67, v67, v78
	v_pk_mul_f32 v[68:69], v[76:77], v[68:69]
	v_pk_mul_f32 v[70:71], v[76:77], v[70:71]
	v_pk_mul_f32 v[72:73], v[76:77], v[72:73]
	v_pk_mul_f32 v[78:79], v[76:77], v[80:81]
	v_pk_mul_f32 v[80:81], v[76:77], v[84:85]
	v_pk_mul_f32 v[74:75], v[76:77], v[74:75]
	v_pk_mul_f32 v[84:85], v[76:77], v[86:87]
	v_pk_mul_f32 v[76:77], v[76:77], v[88:89]
	v_fma_f32 v69, v67, v92, v69
	v_fma_f32 v71, v67, v93, v71
	v_fma_f32 v73, v67, v94, v73
	v_fma_f32 v79, v67, v95, v79
	v_fma_f32 v81, v67, v96, v81
	v_fma_f32 v75, v67, v97, v75
	v_fma_f32 v85, v67, v98, v85
	v_fma_f32 v67, v67, v99, v77
	v_add_f32_e32 v68, v68, v69
	v_add_f32_e32 v69, v70, v71
	v_add_f32_e32 v70, v72, v73
	v_add_f32_e32 v71, v78, v79
	v_add_f32_e32 v72, v80, v81
	v_add_f32_e32 v73, v74, v75
	v_add_f32_e32 v74, v84, v85
	v_add_f32_e32 v67, v76, v67
	v_cvt_pk_bf16_f32 v68, v68, v69
	v_cvt_pk_bf16_f32 v69, v70, v71
	v_cvt_pk_bf16_f32 v70, v72, v73
	v_cvt_pk_bf16_f32 v71, v74, v67
	global_store_dwordx4 v[82:83], v[68:71], off
	s_branch .LBB0_1296
